# attention block head: counted vmcnt so K1/V1 tile loads stay in flight behind first QK; tail odd path waits only for V DMA (vmcnt 12)
# baseline (speedup 1.0000x reference)
.LBB0_383:
	s_ashr_i32 s13, s33, 6
	v_and_b32_e32 v212, 31, v49
	s_lshl_b32 s48, s13, 5
	v_lshlrev_b32_e32 v2, 2, v66
	v_sub_u32_e32 v3, v212, v2
	s_add_i32 s1, s48, s8
	v_add_u32_e32 v210, s1, v3
	v_lshlrev_b32_e32 v4, 4, v49
	v_lshlrev_b32_e32 v200, 4, v66
	v_and_b32_e32 v78, 0xf0, v4
	v_lshlrev_b32_e32 v3, 8, v212
	v_xad_u32 v4, v200, v78, 0
	v_add_u32_e32 v214, v4, v3
	v_or_b32_e32 v196, 0x80, v200
	v_xad_u32 v196, v196, v78, 0
	v_add_u32_e32 v196, v196, v3
	v_or_b32_e32 v197, 0xa0, v200
	v_xad_u32 v197, v197, v78, 0
	v_add_u32_e32 v197, v197, v3
	v_or_b32_e32 v198, 0xc0, v200
	v_xad_u32 v198, v198, v78, 0
	v_add_u32_e32 v198, v198, v3
	v_or_b32_e32 v199, 0xe0, v200
	v_xad_u32 v199, v199, v78, 0
	v_add_u32_e32 v199, v199, v3
	ds_read_b128 v[4:7], v214 offset:32768
	ds_read_b128 v[8:11], v196 offset:32768
	v_or_b32_e32 v12, 32, v200
	s_waitcnt vmcnt(6) lgkmcnt(1)
	s_cbranch_vccz .Lhd_w1
	s_waitcnt vmcnt(2)
.Lhd_w1:
	v_mfma_f32_32x32x16_bf16 v[32:47], v[4:7], v[158:161], v[32:47]
	ds_read_b128 v[4:7], v214 offset:40960
	v_xad_u32 v12, v12, v78, 0
	v_add_u32_e32 v215, v12, v3
	ds_read_b128 v[12:15], v196 offset:40960
	v_or_b32_e32 v70, 64, v200
	v_xad_u32 v70, v70, v78, 0
	v_add_u32_e32 v216, v70, v3
	s_waitcnt vmcnt(4) lgkmcnt(1)
	s_cbranch_vccz .Lhd_w2
	s_waitcnt vmcnt(0)
.Lhd_w2:
	v_mfma_f32_32x32x16_bf16 v[16:31], v[4:7], v[158:161], v[16:31]
	ds_read_b128 v[4:7], v215 offset:32768
	ds_read_b128 v[66:69], v197 offset:32768
	ds_read_b128 v[70:73], v197 offset:40960
	v_or_b32_e32 v79, 0x60, v200
	v_xad_u32 v78, v79, v78, 0
	v_add_u32_e32 v217, v78, v3
	s_or_b32 s6, s49, 63
	s_cmp_le_i32 s6, s1
	s_waitcnt lgkmcnt(2)
	v_mfma_f32_32x32x16_bf16 v[32:47], v[4:7], v[154:157], v[32:47]
	ds_read_b128 v[4:7], v215 offset:40960
	s_cselect_b64 s[6:7], -1, 0
	s_add_i32 s8, s1, 0xfffff01f
	s_cmp_gt_i32 s49, s8
	s_cselect_b64 s[80:81], -1, 0
	s_and_b64 s[6:7], s[6:7], s[80:81]
	s_and_b64 vcc, exec, s[6:7]
	s_waitcnt lgkmcnt(0)
	v_mfma_f32_32x32x16_bf16 v[16:31], v[4:7], v[154:157], v[16:31]
	ds_read_b128 v[4:7], v216 offset:32768
	ds_read_b128 v[74:77], v198 offset:32768
	ds_read_b128 v[78:81], v198 offset:40960
	s_waitcnt lgkmcnt(2)
	v_mfma_f32_32x32x16_bf16 v[32:47], v[4:7], v[150:153], v[32:47]
	ds_read_b128 v[4:7], v216 offset:40960
	s_waitcnt lgkmcnt(0)
	v_mfma_f32_32x32x16_bf16 v[16:31], v[4:7], v[150:153], v[16:31]
	ds_read_b128 v[4:7], v217 offset:32768
	ds_read_b128 v[114:117], v199 offset:32768
	s_waitcnt lgkmcnt(1)
	v_mfma_f32_32x32x16_bf16 v[32:47], v[4:7], v[146:149], v[32:47]
	ds_read_b128 v[4:7], v217 offset:40960
	ds_read_b128 v[118:121], v199 offset:40960
	s_waitcnt lgkmcnt(1)
	v_mfma_f32_32x32x16_bf16 v[16:31], v[4:7], v[146:149], v[16:31]
	v_mfma_f32_32x32x16_bf16 v[32:47], v[8:11], v[142:145], v[32:47]
	v_mfma_f32_32x32x16_bf16 v[16:31], v[12:15], v[142:145], v[16:31]
	v_mfma_f32_32x32x16_bf16 v[32:47], v[66:69], v[138:141], v[32:47]
	v_mfma_f32_32x32x16_bf16 v[16:31], v[70:73], v[138:141], v[16:31]
	v_mfma_f32_32x32x16_bf16 v[32:47], v[74:77], v[134:137], v[32:47]
	v_mfma_f32_32x32x16_bf16 v[16:31], v[78:81], v[134:137], v[16:31]
	v_mfma_f32_32x32x16_bf16 v[32:47], v[114:117], v[130:133], v[32:47]
	s_waitcnt lgkmcnt(0)
	v_mfma_f32_32x32x16_bf16 v[16:31], v[118:121], v[130:133], v[16:31]
	s_cbranch_vccnz .LBB0_385
	v_subrev_u32_e32 v3, s49, v210
	v_cmp_gt_u32_e32 vcc, s11, v3
	v_add_u32_e32 v4, 0xffffefe0, v3
	s_nop 5
	v_cndmask_b32_e32 v32, v202, v32, vcc
	v_cmp_lt_u32_e32 vcc, s68, v4
	v_add_u32_e32 v4, 0xffffefff, v3
	s_nop 0
	v_cndmask_b32_e32 v16, v202, v16, vcc
	v_cmp_lt_u32_e32 vcc, s68, v4
	v_add_u32_e32 v4, 0xffffefdf, v3
	s_nop 0
	v_cndmask_b32_e32 v33, v202, v33, vcc
	v_cmp_lt_u32_e32 vcc, s68, v4
	v_add_u32_e32 v4, 0xffffeffe, v3
	s_nop 0
	v_cndmask_b32_e32 v17, v202, v17, vcc
	v_cmp_lt_u32_e32 vcc, s68, v4
	v_add_u32_e32 v4, 0xffffefde, v3
	s_nop 0
	v_cndmask_b32_e32 v34, v202, v34, vcc
	v_cmp_lt_u32_e32 vcc, s68, v4
	v_add_u32_e32 v4, 0xffffeffd, v3
	s_nop 0
	v_cndmask_b32_e32 v18, v202, v18, vcc
	v_cmp_lt_u32_e32 vcc, s68, v4
	v_add_u32_e32 v4, 0xffffefdd, v3
	s_nop 0
	v_cndmask_b32_e32 v35, v202, v35, vcc
	v_cmp_lt_u32_e32 vcc, s68, v4
	v_add_u32_e32 v4, 0xffffeff8, v3
	s_nop 0
	v_cndmask_b32_e32 v19, v202, v19, vcc
	v_cmp_lt_u32_e32 vcc, s68, v4
	v_add_u32_e32 v4, 0xffffefd8, v3
	s_nop 0
	v_cndmask_b32_e32 v36, v202, v36, vcc
	v_cmp_lt_u32_e32 vcc, s68, v4
	v_add_u32_e32 v4, 0xffffeff7, v3
	s_nop 0
	v_cndmask_b32_e32 v20, v202, v20, vcc
	v_cmp_lt_u32_e32 vcc, s68, v4
	v_add_u32_e32 v4, 0xffffefd7, v3
	s_nop 0
	v_cndmask_b32_e32 v37, v202, v37, vcc
	v_cmp_lt_u32_e32 vcc, s68, v4
	v_add_u32_e32 v4, 0xffffeff6, v3
	s_nop 0
	v_cndmask_b32_e32 v21, v202, v21, vcc
	v_cmp_lt_u32_e32 vcc, s68, v4
	v_add_u32_e32 v4, 0xffffefd6, v3
	s_nop 0
	v_cndmask_b32_e32 v38, v202, v38, vcc
	v_cmp_lt_u32_e32 vcc, s68, v4
	v_add_u32_e32 v4, 0xffffeff5, v3
	s_nop 0
	v_cndmask_b32_e32 v22, v202, v22, vcc
	v_cmp_lt_u32_e32 vcc, s68, v4
	v_add_u32_e32 v4, 0xffffefd5, v3
	s_nop 0
	v_cndmask_b32_e32 v39, v202, v39, vcc
	v_cmp_lt_u32_e32 vcc, s68, v4
	v_add_u32_e32 v4, 0xffffeff0, v3
	s_nop 0
	v_cndmask_b32_e32 v23, v202, v23, vcc
	v_cmp_lt_u32_e32 vcc, s68, v4
	v_add_u32_e32 v4, 0xffffefd0, v3
	s_nop 0
	v_cndmask_b32_e32 v40, v202, v40, vcc
	v_cmp_lt_u32_e32 vcc, s68, v4
	v_add_u32_e32 v4, 0xffffefef, v3
	s_nop 0
	v_cndmask_b32_e32 v24, v202, v24, vcc
	v_cmp_lt_u32_e32 vcc, s68, v4
	v_add_u32_e32 v4, 0xffffefcf, v3
	s_nop 0
	v_cndmask_b32_e32 v41, v202, v41, vcc
	v_cmp_lt_u32_e32 vcc, s68, v4
	v_add_u32_e32 v4, 0xffffefee, v3
	s_nop 0
	v_cndmask_b32_e32 v25, v202, v25, vcc
	v_cmp_lt_u32_e32 vcc, s68, v4
	v_add_u32_e32 v4, 0xffffefce, v3
	s_nop 0
	v_cndmask_b32_e32 v42, v202, v42, vcc
	v_cmp_lt_u32_e32 vcc, s68, v4
	v_add_u32_e32 v4, 0xffffefed, v3
	s_nop 0
	v_cndmask_b32_e32 v26, v202, v26, vcc
	v_cmp_lt_u32_e32 vcc, s68, v4
	v_add_u32_e32 v4, 0xffffefcd, v3
	s_nop 0
	v_cndmask_b32_e32 v43, v202, v43, vcc
	v_cmp_lt_u32_e32 vcc, s68, v4
	v_add_u32_e32 v4, 0xffffefe8, v3
	s_nop 0
	v_cndmask_b32_e32 v27, v202, v27, vcc
	v_cmp_lt_u32_e32 vcc, s68, v4
	v_add_u32_e32 v4, 0xffffefc8, v3
	s_nop 0
	v_cndmask_b32_e32 v44, v202, v44, vcc
	v_cmp_lt_u32_e32 vcc, s68, v4
	v_add_u32_e32 v4, 0xffffefe7, v3
	s_nop 0
	v_cndmask_b32_e32 v28, v202, v28, vcc
	v_cmp_lt_u32_e32 vcc, s68, v4
	v_add_u32_e32 v4, 0xffffefc7, v3
	s_nop 0
	v_cndmask_b32_e32 v45, v202, v45, vcc
	v_cmp_lt_u32_e32 vcc, s68, v4
	v_add_u32_e32 v4, 0xffffefe6, v3
	s_nop 0
	v_cndmask_b32_e32 v29, v202, v29, vcc
	v_cmp_lt_u32_e32 vcc, s68, v4
	v_add_u32_e32 v4, 0xffffefc6, v3
	s_nop 0
	v_cndmask_b32_e32 v46, v202, v46, vcc
	v_cmp_lt_u32_e32 vcc, s68, v4
	v_add_u32_e32 v4, 0xffffefe5, v3
	v_add_u32_e32 v3, 0xffffefc5, v3
	v_cndmask_b32_e32 v30, v202, v30, vcc
	v_cmp_lt_u32_e32 vcc, s68, v4
	s_nop 1
	v_cndmask_b32_e32 v47, v202, v47, vcc
	v_cmp_lt_u32_e32 vcc, s68, v3
	s_nop 1
	v_cndmask_b32_e32 v31, v202, v31, vcc

.LBB0_416:
	s_waitcnt vmcnt(12)
	v_max_f32_e32 v114, v51, v51
	v_max_f32_e32 v115, v50, v50
	v_max_f32_e32 v114, v115, v114
	v_max3_f32 v114, v114, v52, v53
	v_max3_f32 v114, v114, v54, v55
	v_max3_f32 v114, v114, v56, v57
	v_max3_f32 v114, v114, v58, v59
	v_max3_f32 v114, v114, v60, v61
	v_max3_f32 v114, v114, v62, v63
	v_max3_f32 v114, v114, v64, v65
	v_max3_f32 v114, v114, v82, v83
	v_max3_f32 v114, v114, v84, v85
	v_max3_f32 v114, v114, v86, v87
	v_max3_f32 v114, v114, v88, v89
	v_max3_f32 v114, v114, v90, v91
	v_max3_f32 v114, v114, v92, v93
	v_max3_f32 v114, v114, v94, v95
	v_max3_f32 v114, v114, v96, v97
	v_mov_b32_e32 v115, v114
	s_nop 1
	v_permlane32_swap_b32_e32 v114, v115
	v_max_f32_e32 v115, v115, v115
	v_max_f32_e32 v114, v114, v114
	v_max_f32_e32 v114, v114, v115
	v_max_f32_e32 v116, v182, v182
	v_sub_f32_e32 v115, v114, v182
	v_max_f32_e32 v114, v116, v114
	v_sub_f32_e32 v116, v182, v114
	v_mul_f32_e32 v116, 0x3e0293ee, v116
	v_mul_f32_e32 v115, 0x3db504f3, v115
	v_exp_f32_e32 v116, v116
	v_cmp_ge_f32_e32 vcc, s69, v115
	s_cmp_eq_u64 vcc, exec
	s_cselect_b64 s[4:5], -1, 0
	v_cndmask_b32_e64 v178, v116, 1.0, s[4:5]
	v_cmp_gt_f32_e32 vcc, 1.0, v178
	s_barrier
	s_cbranch_vccz .LBB0_420
	v_cmp_gt_u32_e32 vcc, 32, v206
	s_and_saveexec_b64 s[50:51], vcc
	ds_write_b32 v208, v178 offset:128
	s_or_b64 exec, exec, s[50:51]
	s_waitcnt lgkmcnt(0)
	ds_read_b128 v[116:119], v207 offset:224
	ds_read_b128 v[120:123], v207 offset:192
	ds_read_b128 v[124:127], v207 offset:160
	ds_read_b128 v[162:165], v207 offset:128
	s_waitcnt lgkmcnt(3)
	v_pk_mul_f32 v[80:81], v[80:81], v[118:119]
	s_waitcnt lgkmcnt(2)
	v_pk_mul_f32 v[76:77], v[76:77], v[122:123]
	s_waitcnt lgkmcnt(1)
	v_pk_mul_f32 v[72:73], v[72:73], v[126:127]
	s_waitcnt lgkmcnt(0)
	v_pk_mul_f32 v[68:69], v[68:69], v[164:165]
	v_pk_mul_f32 v[78:79], v[78:79], v[116:117]
	v_pk_mul_f32 v[74:75], v[74:75], v[120:121]
	v_pk_mul_f32 v[70:71], v[70:71], v[124:125]
	v_pk_mul_f32 v[66:67], v[66:67], v[162:163]
	v_pk_mul_f32 v[48:49], v[48:49], v[118:119]
	v_pk_mul_f32 v[44:45], v[44:45], v[122:123]
	v_pk_mul_f32 v[40:41], v[40:41], v[126:127]
	v_pk_mul_f32 v[36:37], v[36:37], v[164:165]
	v_pk_mul_f32 v[46:47], v[46:47], v[116:117]
	v_pk_mul_f32 v[42:43], v[42:43], v[120:121]
	v_pk_mul_f32 v[38:39], v[38:39], v[124:125]
	v_pk_mul_f32 v[34:35], v[34:35], v[162:163]
	v_pk_mul_f32 v[32:33], v[32:33], v[118:119]
	v_pk_mul_f32 v[28:29], v[28:29], v[122:123]
	v_pk_mul_f32 v[24:25], v[24:25], v[126:127]
	v_pk_mul_f32 v[20:21], v[20:21], v[164:165]
	v_pk_mul_f32 v[30:31], v[30:31], v[116:117]
	v_pk_mul_f32 v[26:27], v[26:27], v[120:121]
	v_pk_mul_f32 v[22:23], v[22:23], v[124:125]
	v_pk_mul_f32 v[18:19], v[18:19], v[162:163]
	v_pk_mul_f32 v[16:17], v[16:17], v[118:119]
	v_pk_mul_f32 v[12:13], v[12:13], v[122:123]
	v_pk_mul_f32 v[8:9], v[8:9], v[126:127]
	v_pk_mul_f32 v[4:5], v[4:5], v[164:165]
	v_pk_mul_f32 v[14:15], v[14:15], v[116:117]
	v_pk_mul_f32 v[10:11], v[10:11], v[120:121]
	v_pk_mul_f32 v[6:7], v[6:7], v[124:125]
	v_pk_mul_f32 v[2:3], v[2:3], v[162:163]
